# combination: v119 (solve-block address copies removed, all conversions via v_cvt_pk_bf16_f32) + rows 2-3 LDS reads issued at solve-block entry
# speedup vs baseline: 1.0035x; 1.0034x over previous
.LBB0_355:
	s_and_b64 vcc, exec, s[18:19]
	s_cbranch_vccz .LBB0_421
	v_add_u32_e32 v2, v171, v187
	ds_read_b128 v[4:7], v2 offset:272
	v_mov_b32_e32 v2, v188
	ds_read_b128 v[18:21], v2 offset:544
	ds_read_b128 v[22:25], v2 offset:816
	s_waitcnt lgkmcnt(2)
	v_fma_f32 v17, -v195, v4, v196
	s_nop 0
	s_waitcnt lgkmcnt(1)
	v_fma_f32 v3, -v195, v18, v197
	v_fma_f32 v4, -v19, v17, 0
	v_add_f32_e32 v15, v4, v3
	s_nop 0
	ds_read_b128 v[4:7], v2 offset:1088
	s_waitcnt lgkmcnt(1)
	v_fma_f32 v3, -v195, v22, v198
	v_fma_f32 v8, -v17, v23, 0
	v_fma_f32 v9, -v24, v15, 0
	v_add_f32_e32 v3, v8, v3
	v_add_f32_e32 v13, v9, v3
	s_nop 0
	ds_read_b128 v[18:21], v2 offset:1360
	ds_read_b128 v[8:11], v2 offset:1376
	s_waitcnt lgkmcnt(2)
	v_fma_f32 v3, -v195, v4, v199
	v_fma_f32 v4, -v17, v5, 0
	v_fma_f32 v5, -v15, v6, 0
	v_fma_f32 v6, -v7, v13, 0
	v_add_f32_e32 v3, v4, v3
	v_add_f32_e32 v4, v6, v5
	s_waitcnt lgkmcnt(0)
	v_add_f32_e32 v11, v4, v3
	v_fma_f32 v9, -v17, v19, 0
	ds_read_b128 v[4:7], v2 offset:1632
	ds_read_b128 v[22:25], v2 offset:1648
	v_fma_f32 v3, -v195, v18, v200
	v_fma_f32 v10, -v15, v20, 0
	v_fma_f32 v12, -v13, v21, 0
	v_fma_f32 v3, -v8, v11, v3
	v_add_f32_e32 v3, v9, v3
	v_add_f32_e32 v8, v12, v10
	v_add_f32_e32 v9, v8, v3
	s_nop 0
	ds_read_b128 v[18:21], v2 offset:1904
	ds_read_b128 v[28:31], v2 offset:1920
	s_waitcnt lgkmcnt(3)
	v_fma_f32 v3, -v195, v4, v201
	v_fma_f32 v4, -v17, v5, 0
	v_fma_f32 v5, -v15, v6, 0
	v_fma_f32 v6, -v13, v7, 0
	s_waitcnt lgkmcnt(2)
	v_fma_f32 v3, -v11, v22, v3
	v_fma_f32 v4, -v23, v9, v4
	v_add_f32_e32 v3, v4, v3
	v_add_f32_e32 v4, v6, v5
	v_add_f32_e32 v7, v4, v3
	s_waitcnt lgkmcnt(1)
	v_fma_f32 v4, -v17, v19, 0
	ds_read_b128 v[22:25], v2 offset:2176
	ds_read_b128 v[32:35], v2 offset:2192
	v_fma_f32 v3, -v195, v18, v202
	v_fma_f32 v5, -v15, v20, 0
	v_fma_f32 v6, -v13, v21, 0
	s_waitcnt lgkmcnt(2)
	v_fma_f32 v3, -v11, v28, v3
	v_fma_f32 v4, -v9, v29, v4
	v_fma_f32 v5, -v30, v7, v5
	v_add_f32_e32 v3, v4, v3
	v_add_f32_e32 v4, v6, v5
	v_add_f32_e32 v4, v4, v3
	s_waitcnt lgkmcnt(1)
	v_fma_f32 v5, -v17, v23, 0
	ds_read_b128 v[18:21], v2 offset:2448
	ds_read_b128 v[28:31], v2 offset:2464
	ds_read_b128 v[36:39], v2 offset:2480
	v_fma_f32 v3, -v195, v22, v203
	v_fma_f32 v6, -v15, v24, 0
	v_fma_f32 v8, -v13, v25, 0
	s_waitcnt lgkmcnt(3)
	v_fma_f32 v3, -v11, v32, v3
	v_fma_f32 v5, -v9, v33, v5
	v_fma_f32 v6, -v7, v34, v6
	v_fma_f32 v8, -v35, v4, v8
	v_add_f32_e32 v3, v5, v3
	v_add_f32_e32 v5, v8, v6
	v_add_f32_e32 v5, v5, v3
	s_waitcnt lgkmcnt(2)
	v_fma_f32 v6, -v17, v19, 0
	ds_read_b128 v[22:25], v2 offset:2720
	ds_read_b128 v[32:35], v2 offset:2736
	s_waitcnt lgkmcnt(2)
	ds_read_b128 v[38:41], v2 offset:2752
	v_fma_f32 v3, -v195, v18, v204
	v_fma_f32 v8, -v15, v20, 0
	v_fma_f32 v10, -v13, v21, 0
	v_fma_f32 v3, -v11, v28, v3
	v_fma_f32 v6, -v9, v29, v6
	v_fma_f32 v8, -v7, v30, v8
	v_fma_f32 v10, -v4, v31, v10
	v_fma_f32 v3, -v36, v5, v3
	v_add_f32_e32 v3, v6, v3
	v_add_f32_e32 v6, v10, v8
	v_add_f32_e32 v6, v6, v3
	s_waitcnt lgkmcnt(2)
	v_fma_f32 v8, -v17, v23, 0
	ds_read_b128 v[18:21], v2 offset:2992
	ds_read_b128 v[28:31], v2 offset:3008
	s_waitcnt lgkmcnt(2)
	ds_read_b128 v[40:43], v2 offset:3024
	v_fma_f32 v3, -v195, v22, v205
	v_fma_f32 v10, -v15, v24, 0
	v_fma_f32 v12, -v13, v25, 0
	v_fma_f32 v3, -v11, v32, v3
	v_fma_f32 v8, -v9, v33, v8
	v_fma_f32 v10, -v7, v34, v10
	v_fma_f32 v12, -v4, v35, v12
	v_fma_f32 v3, -v5, v38, v3
	v_fma_f32 v8, -v39, v6, v8
	v_add_f32_e32 v3, v8, v3
	v_add_f32_e32 v8, v12, v10
	v_add_f32_e32 v8, v8, v3
	s_waitcnt lgkmcnt(2)
	v_fma_f32 v10, -v17, v19, 0
	ds_read_b128 v[22:25], v2 offset:3264
	ds_read_b128 v[32:35], v2 offset:3280
	ds_read_b128 v[36:39], v2 offset:3296
	v_fma_f32 v3, -v195, v18, v206
	v_fma_f32 v12, -v15, v20, 0
	v_fma_f32 v14, -v13, v21, 0
	s_waitcnt lgkmcnt(4)
	v_fma_f32 v3, -v11, v28, v3
	v_fma_f32 v10, -v9, v29, v10
	v_fma_f32 v12, -v7, v30, v12
	v_fma_f32 v14, -v4, v31, v14
	s_waitcnt lgkmcnt(3)
	v_fma_f32 v3, -v5, v40, v3
	v_fma_f32 v10, -v6, v41, v10
	v_fma_f32 v12, -v42, v8, v12
	v_add_f32_e32 v3, v10, v3
	v_add_f32_e32 v10, v14, v12
	v_add_f32_e32 v10, v10, v3
	s_waitcnt lgkmcnt(2)
	v_fma_f32 v12, -v17, v23, 0
	ds_read_b128 v[18:21], v2 offset:3536
	ds_read_b128 v[28:31], v2 offset:3552
	ds_read_b128 v[40:43], v2 offset:3568
	ds_read_b128 v[44:47], v2 offset:3584
	v_fma_f32 v3, -v195, v22, v207
	v_fma_f32 v14, -v15, v24, 0
	v_fma_f32 v16, -v13, v25, 0
	s_waitcnt lgkmcnt(5)
	v_fma_f32 v3, -v11, v32, v3
	v_fma_f32 v12, -v9, v33, v12
	v_fma_f32 v14, -v7, v34, v14
	v_fma_f32 v16, -v4, v35, v16
	s_waitcnt lgkmcnt(4)
	v_fma_f32 v3, -v5, v36, v3
	v_fma_f32 v12, -v6, v37, v12
	v_fma_f32 v14, -v8, v38, v14
	v_fma_f32 v16, -v39, v10, v16
	v_add_f32_e32 v3, v12, v3
	v_add_f32_e32 v12, v16, v14
	v_add_f32_e32 v12, v12, v3
	s_waitcnt lgkmcnt(3)
	v_fma_f32 v14, -v17, v19, 0
	ds_read_b128 v[22:25], v2 offset:3808
	ds_read_b128 v[32:35], v2 offset:3824
	ds_read_b128 v[36:39], v2 offset:3840
	s_waitcnt lgkmcnt(3)
	ds_read_b128 v[46:49], v2 offset:3856
	v_fma_f32 v3, -v195, v18, v208
	v_fma_f32 v16, -v15, v20, 0
	v_fma_f32 v18, -v13, v21, 0
	v_fma_f32 v3, -v11, v28, v3
	v_fma_f32 v14, -v9, v29, v14
	v_fma_f32 v16, -v7, v30, v16
	v_fma_f32 v18, -v4, v31, v18
	v_fma_f32 v3, -v5, v40, v3
	v_fma_f32 v14, -v6, v41, v14
	v_fma_f32 v16, -v8, v42, v16
	v_fma_f32 v18, -v10, v43, v18
	v_fma_f32 v3, -v44, v12, v3
	v_add_f32_e32 v3, v14, v3
	v_add_f32_e32 v14, v18, v16
	v_add_f32_e32 v14, v14, v3
	s_waitcnt lgkmcnt(3)
	v_fma_f32 v16, -v17, v23, 0
	ds_read_b128 v[18:21], v2 offset:4080
	ds_read_b128 v[28:31], v2 offset:4096
	ds_read_b128 v[40:43], v2 offset:4112
	s_waitcnt lgkmcnt(3)
	ds_read_b128 v[48:51], v2 offset:4128
	v_fma_f32 v3, -v195, v22, v209
	v_fma_f32 v22, -v15, v24, 0
	v_fma_f32 v23, -v13, v25, 0
	v_fma_f32 v3, -v11, v32, v3
	v_fma_f32 v16, -v9, v33, v16
	v_fma_f32 v22, -v7, v34, v22
	v_fma_f32 v23, -v4, v35, v23
	v_fma_f32 v3, -v5, v36, v3
	v_fma_f32 v16, -v6, v37, v16
	v_fma_f32 v22, -v8, v38, v22
	v_fma_f32 v23, -v10, v39, v23
	v_fma_f32 v3, -v12, v46, v3
	v_fma_f32 v16, -v47, v14, v16
	v_add_f32_e32 v3, v16, v3
	v_add_f32_e32 v16, v23, v22
	v_add_f32_e32 v16, v16, v3
	s_nop 0
	ds_read_b128 v[22:25], v2 offset:4352
	ds_read_b128 v[32:35], v2 offset:4368
	ds_read_b128 v[36:39], v2 offset:4384
	ds_read_b128 v[44:47], v2 offset:4400
	s_waitcnt lgkmcnt(7)
	v_fma_f32 v3, -v195, v18, v210
	v_fma_f32 v18, -v17, v19, 0
	v_fma_f32 v19, -v15, v20, 0
	v_fma_f32 v20, -v13, v21, 0
	s_waitcnt lgkmcnt(6)
	v_fma_f32 v3, -v11, v28, v3
	v_fma_f32 v18, -v9, v29, v18
	v_fma_f32 v19, -v7, v30, v19
	v_fma_f32 v20, -v4, v31, v20
	s_waitcnt lgkmcnt(5)
	v_fma_f32 v3, -v5, v40, v3
	v_fma_f32 v18, -v6, v41, v18
	v_fma_f32 v19, -v8, v42, v19
	v_fma_f32 v20, -v10, v43, v20
	s_waitcnt lgkmcnt(4)
	v_fma_f32 v3, -v12, v48, v3
	v_fma_f32 v18, -v14, v49, v18
	v_fma_f32 v19, -v50, v16, v19
	v_add_f32_e32 v3, v18, v3
	v_add_f32_e32 v18, v20, v19
	v_add_f32_e32 v18, v18, v3
	s_waitcnt lgkmcnt(3)
	v_fma_f32 v19, -v17, v23, 0
	ds_read_b128 v[28:31], v2 offset:4624
	ds_read_b128 v[40:43], v2 offset:4640
	ds_read_b128 v[48:51], v2 offset:4656
	ds_read_b128 v[52:55], v2 offset:4672
	ds_read_b128 v[56:59], v2 offset:4688
	v_fma_f32 v3, -v195, v22, v211
	v_fma_f32 v20, -v15, v24, 0
	v_fma_f32 v21, -v13, v25, 0
	s_waitcnt lgkmcnt(7)
	v_fma_f32 v3, -v11, v32, v3
	v_fma_f32 v19, -v9, v33, v19
	v_fma_f32 v20, -v7, v34, v20
	v_fma_f32 v21, -v4, v35, v21
	s_waitcnt lgkmcnt(6)
	v_fma_f32 v3, -v5, v36, v3
	v_fma_f32 v19, -v6, v37, v19
	v_fma_f32 v20, -v8, v38, v20
	v_fma_f32 v21, -v10, v39, v21
	s_waitcnt lgkmcnt(5)
	v_fma_f32 v3, -v12, v44, v3
	v_fma_f32 v19, -v14, v45, v19
	v_fma_f32 v20, -v16, v46, v20
	v_fma_f32 v21, -v47, v18, v21
	v_add_f32_e32 v3, v19, v3
	v_add_f32_e32 v19, v21, v20
	v_add_f32_e32 v19, v19, v3
	s_waitcnt lgkmcnt(4)
	v_fma_f32 v20, -v17, v29, 0
	ds_read_b128 v[22:25], v2 offset:4896
	ds_read_b128 v[32:35], v2 offset:4912
	ds_read_b128 v[36:39], v2 offset:4928
	ds_read_b128 v[44:47], v2 offset:4944
	s_waitcnt lgkmcnt(4)
	ds_read_b128 v[58:61], v2 offset:4960
	v_fma_f32 v3, -v195, v28, v212
	v_fma_f32 v21, -v15, v30, 0
	v_fma_f32 v27, -v13, v31, 0
	v_fma_f32 v3, -v11, v40, v3
	v_fma_f32 v20, -v9, v41, v20
	v_fma_f32 v21, -v7, v42, v21
	v_fma_f32 v27, -v4, v43, v27
	v_fma_f32 v3, -v5, v48, v3
	v_fma_f32 v20, -v6, v49, v20
	v_fma_f32 v21, -v8, v50, v21
	v_fma_f32 v27, -v10, v51, v27
	v_fma_f32 v3, -v12, v52, v3
	v_fma_f32 v20, -v14, v53, v20
	v_fma_f32 v21, -v16, v54, v21
	v_fma_f32 v27, -v18, v55, v27
	v_fma_f32 v3, -v56, v19, v3
	v_add_f32_e32 v3, v20, v3
	v_add_f32_e32 v20, v27, v21
	v_add_f32_e32 v20, v20, v3
	s_waitcnt lgkmcnt(4)
	v_fma_f32 v21, -v17, v23, 0
	ds_read_b128 v[28:31], v2 offset:5168
	ds_read_b128 v[40:43], v2 offset:5184
	ds_read_b128 v[48:51], v2 offset:5200
	ds_read_b128 v[52:55], v2 offset:5216
	s_waitcnt lgkmcnt(4)
	ds_read_b128 v[60:63], v2 offset:5232
	v_fma_f32 v3, -v195, v22, v213
	v_fma_f32 v22, -v15, v24, 0
	v_fma_f32 v23, -v13, v25, 0
	v_fma_f32 v3, -v11, v32, v3
	v_fma_f32 v21, -v9, v33, v21
	v_fma_f32 v22, -v7, v34, v22
	v_fma_f32 v23, -v4, v35, v23
	v_fma_f32 v3, -v5, v36, v3
	v_fma_f32 v21, -v6, v37, v21
	v_fma_f32 v22, -v8, v38, v22
	v_fma_f32 v23, -v10, v39, v23
	v_fma_f32 v3, -v12, v44, v3
	v_fma_f32 v21, -v14, v45, v21
	v_fma_f32 v22, -v16, v46, v22
	v_fma_f32 v23, -v18, v47, v23
	v_fma_f32 v3, -v19, v58, v3
	v_fma_f32 v21, -v59, v20, v21
	v_add_f32_e32 v3, v21, v3
	v_add_f32_e32 v21, v23, v22
	v_add_f32_e32 v21, v21, v3
	s_waitcnt lgkmcnt(4)
	v_fma_f32 v22, -v17, v29, 0
	ds_read_b128 v[32:35], v2 offset:5440
	ds_read_b128 v[36:39], v2 offset:5456
	ds_read_b128 v[44:47], v2 offset:5472
	ds_read_b128 v[56:59], v2 offset:5488
	ds_read_b128 v[64:67], v2 offset:5504
	v_fma_f32 v3, -v195, v28, v214
	v_fma_f32 v23, -v15, v30, 0
	v_fma_f32 v24, -v13, v31, 0
	s_waitcnt lgkmcnt(8)
	v_fma_f32 v3, -v11, v40, v3
	v_fma_f32 v22, -v9, v41, v22
	v_fma_f32 v23, -v7, v42, v23
	v_fma_f32 v24, -v4, v43, v24
	s_waitcnt lgkmcnt(7)
	v_fma_f32 v3, -v5, v48, v3
	v_fma_f32 v22, -v6, v49, v22
	v_fma_f32 v23, -v8, v50, v23
	v_fma_f32 v24, -v10, v51, v24
	s_waitcnt lgkmcnt(6)
	v_fma_f32 v3, -v12, v52, v3
	v_fma_f32 v22, -v14, v53, v22
	v_fma_f32 v23, -v16, v54, v23
	v_fma_f32 v24, -v18, v55, v24
	s_waitcnt lgkmcnt(5)
	v_fma_f32 v3, -v19, v60, v3
	v_fma_f32 v22, -v20, v61, v22
	v_fma_f32 v23, -v62, v21, v23
	v_add_f32_e32 v3, v22, v3
	v_add_f32_e32 v22, v24, v23
	v_add_f32_e32 v22, v22, v3
	s_waitcnt lgkmcnt(4)
	v_fma_f32 v23, -v17, v33, 0
	ds_read_b128 v[28:31], v2 offset:5712
	ds_read_b128 v[40:43], v2 offset:5728
	ds_read_b128 v[48:51], v2 offset:5744
	ds_read_b128 v[52:55], v2 offset:5760
	ds_read_b128 v[60:63], v2 offset:5776
	ds_read_b128 v[68:71], v2 offset:5792
	v_fma_f32 v3, -v195, v32, v215
	v_fma_f32 v24, -v15, v34, 0
	v_fma_f32 v25, -v13, v35, 0
	s_waitcnt lgkmcnt(9)
	v_fma_f32 v3, -v11, v36, v3
	v_fma_f32 v23, -v9, v37, v23
	v_fma_f32 v24, -v7, v38, v24
	v_fma_f32 v25, -v4, v39, v25
	s_waitcnt lgkmcnt(8)
	v_fma_f32 v3, -v5, v44, v3
	v_fma_f32 v23, -v6, v45, v23
	v_fma_f32 v24, -v8, v46, v24
	v_fma_f32 v25, -v10, v47, v25
	s_waitcnt lgkmcnt(7)
	v_fma_f32 v3, -v12, v56, v3
	v_fma_f32 v23, -v14, v57, v23
	v_fma_f32 v24, -v16, v58, v24
	v_fma_f32 v25, -v18, v59, v25
	s_waitcnt lgkmcnt(6)
	v_fma_f32 v3, -v19, v64, v3
	v_fma_f32 v23, -v20, v65, v23
	v_fma_f32 v24, -v21, v66, v24
	v_fma_f32 v25, -v67, v22, v25
	v_add_f32_e32 v3, v23, v3
	v_add_f32_e32 v23, v25, v24
	v_add_f32_e32 v23, v23, v3
	s_waitcnt lgkmcnt(5)
	v_fma_f32 v24, -v17, v29, 0
	ds_read_b128 v[32:35], v2 offset:5984
	ds_read_b128 v[36:39], v2 offset:6000
	ds_read_b128 v[44:47], v2 offset:6016
	ds_read_b128 v[56:59], v2 offset:6032
	ds_read_b128 v[64:67], v2 offset:6048
	s_waitcnt lgkmcnt(5)
	ds_read_b128 v[70:73], v2 offset:6064
	v_fma_f32 v3, -v195, v28, v216
	v_fma_f32 v25, -v15, v30, 0
	v_fma_f32 v27, -v13, v31, 0
	v_fma_f32 v3, -v11, v40, v3
	v_fma_f32 v24, -v9, v41, v24
	v_fma_f32 v25, -v7, v42, v25
	v_fma_f32 v27, -v4, v43, v27
	v_fma_f32 v3, -v5, v48, v3
	v_fma_f32 v24, -v6, v49, v24
	v_fma_f32 v25, -v8, v50, v25
	v_fma_f32 v27, -v10, v51, v27
	v_fma_f32 v3, -v12, v52, v3
	v_fma_f32 v24, -v14, v53, v24
	v_fma_f32 v25, -v16, v54, v25
	v_fma_f32 v27, -v18, v55, v27
	v_fma_f32 v3, -v19, v60, v3
	v_fma_f32 v24, -v20, v61, v24
	v_fma_f32 v25, -v21, v62, v25
	v_fma_f32 v27, -v22, v63, v27
	v_fma_f32 v3, -v68, v23, v3
	v_add_f32_e32 v3, v24, v3
	v_add_f32_e32 v24, v27, v25
	v_add_f32_e32 v24, v24, v3
	s_waitcnt lgkmcnt(5)
	v_fma_f32 v25, -v17, v33, 0
	ds_read_b128 v[28:31], v2 offset:6256
	ds_read_b128 v[40:43], v2 offset:6272
	ds_read_b128 v[48:51], v2 offset:6288
	ds_read_b128 v[52:55], v2 offset:6304
	ds_read_b128 v[60:63], v2 offset:6320
	s_waitcnt lgkmcnt(5)
	ds_read_b128 v[72:75], v2 offset:6336
	v_fma_f32 v3, -v195, v32, v217
	v_fma_f32 v27, -v15, v34, 0
	v_fma_f32 v32, -v13, v35, 0
	v_fma_f32 v3, -v11, v36, v3
	v_fma_f32 v25, -v9, v37, v25
	v_fma_f32 v27, -v7, v38, v27
	v_fma_f32 v32, -v4, v39, v32
	v_fma_f32 v3, -v5, v44, v3
	v_fma_f32 v25, -v6, v45, v25
	v_fma_f32 v27, -v8, v46, v27
	v_fma_f32 v32, -v10, v47, v32
	v_fma_f32 v3, -v12, v56, v3
	v_fma_f32 v25, -v14, v57, v25
	v_fma_f32 v27, -v16, v58, v27
	v_fma_f32 v32, -v18, v59, v32
	v_fma_f32 v3, -v19, v64, v3
	v_fma_f32 v25, -v20, v65, v25
	v_fma_f32 v27, -v21, v66, v27
	v_fma_f32 v32, -v22, v67, v32
	v_fma_f32 v3, -v23, v70, v3
	v_fma_f32 v25, -v71, v24, v25
	v_add_f32_e32 v3, v25, v3
	v_add_f32_e32 v25, v32, v27
	v_add_f32_e32 v25, v25, v3
	s_waitcnt lgkmcnt(5)
	v_fma_f32 v27, -v17, v29, 0
	ds_read_b128 v[32:35], v2 offset:6528
	ds_read_b128 v[36:39], v2 offset:6544
	ds_read_b128 v[44:47], v2 offset:6560
	ds_read_b128 v[56:59], v2 offset:6576
	ds_read_b128 v[64:67], v2 offset:6592
	ds_read_b128 v[68:71], v2 offset:6608
	v_fma_f32 v3, -v195, v28, v218
	v_fma_f32 v28, -v15, v30, 0
	v_fma_f32 v29, -v13, v31, 0
	s_waitcnt lgkmcnt(10)
	v_fma_f32 v3, -v11, v40, v3
	v_fma_f32 v27, -v9, v41, v27
	v_fma_f32 v28, -v7, v42, v28
	v_fma_f32 v29, -v4, v43, v29
	s_waitcnt lgkmcnt(9)
	v_fma_f32 v3, -v5, v48, v3
	v_fma_f32 v27, -v6, v49, v27
	v_fma_f32 v28, -v8, v50, v28
	v_fma_f32 v29, -v10, v51, v29
	s_waitcnt lgkmcnt(8)
	v_fma_f32 v3, -v12, v52, v3
	v_fma_f32 v27, -v14, v53, v27
	v_fma_f32 v28, -v16, v54, v28
	v_fma_f32 v29, -v18, v55, v29
	s_waitcnt lgkmcnt(7)
	v_fma_f32 v3, -v19, v60, v3
	v_fma_f32 v27, -v20, v61, v27
	v_fma_f32 v28, -v21, v62, v28
	v_fma_f32 v29, -v22, v63, v29
	s_waitcnt lgkmcnt(6)
	v_fma_f32 v3, -v23, v72, v3
	v_fma_f32 v27, -v24, v73, v27
	v_fma_f32 v28, -v74, v25, v28
	v_add_f32_e32 v3, v27, v3
	v_add_f32_e32 v27, v29, v28
	v_add_f32_e32 v27, v27, v3
	s_waitcnt lgkmcnt(5)
	v_fma_f32 v28, -v17, v33, 0
	ds_read_b128 v[40:43], v2 offset:6800
	ds_read_b128 v[48:51], v2 offset:6816
	ds_read_b128 v[52:55], v2 offset:6832
	ds_read_b128 v[60:63], v2 offset:6848
	ds_read_b128 v[72:75], v2 offset:6864
	ds_read_b128 v[76:79], v2 offset:6880
	ds_read_b128 v[140:143], v2 offset:6896
	v_fma_f32 v3, -v195, v32, v219
	v_fma_f32 v29, -v15, v34, 0
	v_fma_f32 v30, -v13, v35, 0
	s_waitcnt lgkmcnt(11)
	v_fma_f32 v3, -v11, v36, v3
	v_fma_f32 v28, -v9, v37, v28
	v_fma_f32 v29, -v7, v38, v29
	v_fma_f32 v30, -v4, v39, v30
	s_waitcnt lgkmcnt(10)
	v_fma_f32 v3, -v5, v44, v3
	v_fma_f32 v28, -v6, v45, v28
	v_fma_f32 v29, -v8, v46, v29
	v_fma_f32 v30, -v10, v47, v30
	s_waitcnt lgkmcnt(9)
	v_fma_f32 v3, -v12, v56, v3
	v_fma_f32 v28, -v14, v57, v28
	v_fma_f32 v29, -v16, v58, v29
	v_fma_f32 v30, -v18, v59, v30
	s_waitcnt lgkmcnt(8)
	v_fma_f32 v3, -v19, v64, v3
	v_fma_f32 v28, -v20, v65, v28
	v_fma_f32 v29, -v21, v66, v29
	v_fma_f32 v30, -v22, v67, v30
	s_waitcnt lgkmcnt(7)
	v_fma_f32 v3, -v23, v68, v3
	v_fma_f32 v28, -v24, v69, v28
	v_fma_f32 v29, -v25, v70, v29
	v_fma_f32 v30, -v71, v27, v30
	v_add_f32_e32 v3, v28, v3
	v_add_f32_e32 v28, v30, v29
	v_add_f32_e32 v28, v28, v3
	s_waitcnt lgkmcnt(6)
	v_fma_f32 v29, -v17, v41, 0
	ds_read_b128 v[30:33], v2 offset:7072
	ds_read_b128 v[34:37], v2 offset:7088
	ds_read_b128 v[44:47], v2 offset:7104
	ds_read_b128 v[56:59], v2 offset:7120
	ds_read_b128 v[64:67], v2 offset:7136
	ds_read_b128 v[68:71], v2 offset:7152
	s_waitcnt lgkmcnt(6)
	ds_read_b128 v[142:145], v2 offset:7168
	v_fma_f32 v3, -v195, v40, v220
	v_fma_f32 v38, -v15, v42, 0
	v_fma_f32 v39, -v13, v43, 0
	v_fma_f32 v3, -v11, v48, v3
	v_fma_f32 v29, -v9, v49, v29
	v_fma_f32 v38, -v7, v50, v38
	v_fma_f32 v39, -v4, v51, v39
	v_fma_f32 v3, -v5, v52, v3
	v_fma_f32 v29, -v6, v53, v29
	v_fma_f32 v38, -v8, v54, v38
	v_fma_f32 v39, -v10, v55, v39
	v_fma_f32 v3, -v12, v60, v3
	v_fma_f32 v29, -v14, v61, v29
	v_fma_f32 v38, -v16, v62, v38
	v_fma_f32 v39, -v18, v63, v39
	v_fma_f32 v3, -v19, v72, v3
	v_fma_f32 v29, -v20, v73, v29
	v_fma_f32 v38, -v21, v74, v38
	v_fma_f32 v39, -v22, v75, v39
	v_fma_f32 v3, -v23, v76, v3
	v_fma_f32 v29, -v24, v77, v29
	v_fma_f32 v38, -v25, v78, v38
	v_fma_f32 v39, -v27, v79, v39
	v_fma_f32 v3, -v140, v28, v3
	v_add_f32_e32 v3, v29, v3
	v_add_f32_e32 v29, v39, v38
	v_add_f32_e32 v29, v29, v3
	s_nop 0
	ds_read_b128 v[38:41], v2 offset:7344
	ds_read_b128 v[48:51], v2 offset:7360
	ds_read_b128 v[52:55], v2 offset:7376
	ds_read_b128 v[60:63], v2 offset:7392
	ds_read_b128 v[72:75], v2 offset:7408
	ds_read_b128 v[76:79], v2 offset:7424
	s_waitcnt lgkmcnt(6)
	ds_read_b128 v[144:147], v2 offset:7440
	v_fma_f32 v3, -v195, v30, v221
	v_fma_f32 v30, -v17, v31, 0
	v_fma_f32 v31, -v15, v32, 0
	v_fma_f32 v32, -v13, v33, 0
	v_fma_f32 v3, -v11, v34, v3
	v_fma_f32 v30, -v9, v35, v30
	v_fma_f32 v31, -v7, v36, v31
	v_fma_f32 v32, -v4, v37, v32
	v_fma_f32 v3, -v5, v44, v3
	v_fma_f32 v30, -v6, v45, v30
	v_fma_f32 v31, -v8, v46, v31
	v_fma_f32 v32, -v10, v47, v32
	v_fma_f32 v3, -v12, v56, v3
	v_fma_f32 v30, -v14, v57, v30
	v_fma_f32 v31, -v16, v58, v31
	v_fma_f32 v32, -v18, v59, v32
	v_fma_f32 v3, -v19, v64, v3
	v_fma_f32 v30, -v20, v65, v30
	v_fma_f32 v31, -v21, v66, v31
	v_fma_f32 v32, -v22, v67, v32
	v_fma_f32 v3, -v23, v68, v3
	v_fma_f32 v30, -v24, v69, v30
	v_fma_f32 v31, -v25, v70, v31
	v_fma_f32 v32, -v27, v71, v32
	v_fma_f32 v3, -v28, v142, v3
	v_fma_f32 v30, -v143, v29, v30
	v_add_f32_e32 v3, v30, v3
	v_add_f32_e32 v30, v32, v31
	v_add_f32_e32 v30, v30, v3
	s_waitcnt lgkmcnt(6)
	v_fma_f32 v31, -v17, v39, 0
	ds_read_b128 v[32:35], v2 offset:7616
	ds_read_b128 v[42:45], v2 offset:7632
	ds_read_b128 v[56:59], v2 offset:7648
	ds_read_b128 v[64:67], v2 offset:7664
	ds_read_b128 v[68:71], v2 offset:7680
	ds_read_b128 v[140:143], v2 offset:7696
	ds_read_b128 v[148:151], v2 offset:7712
	v_fma_f32 v3, -v195, v38, v222
	v_fma_f32 v36, -v15, v40, 0
	v_fma_f32 v37, -v13, v41, 0
	s_waitcnt lgkmcnt(12)
	v_fma_f32 v3, -v11, v48, v3
	v_fma_f32 v31, -v9, v49, v31
	v_fma_f32 v36, -v7, v50, v36
	v_fma_f32 v37, -v4, v51, v37
	s_waitcnt lgkmcnt(11)
	v_fma_f32 v3, -v5, v52, v3
	v_fma_f32 v31, -v6, v53, v31
	v_fma_f32 v36, -v8, v54, v36
	v_fma_f32 v37, -v10, v55, v37
	s_waitcnt lgkmcnt(10)
	v_fma_f32 v3, -v12, v60, v3
	v_fma_f32 v31, -v14, v61, v31
	v_fma_f32 v36, -v16, v62, v36
	v_fma_f32 v37, -v18, v63, v37
	s_waitcnt lgkmcnt(9)
	v_fma_f32 v3, -v19, v72, v3
	v_fma_f32 v31, -v20, v73, v31
	v_fma_f32 v36, -v21, v74, v36
	v_fma_f32 v37, -v22, v75, v37
	s_waitcnt lgkmcnt(8)
	v_fma_f32 v3, -v23, v76, v3
	v_fma_f32 v31, -v24, v77, v31
	v_fma_f32 v36, -v25, v78, v36
	v_fma_f32 v37, -v27, v79, v37
	s_waitcnt lgkmcnt(7)
	v_fma_f32 v3, -v28, v144, v3
	v_fma_f32 v31, -v29, v145, v31
	v_fma_f32 v36, -v146, v30, v36
	v_add_f32_e32 v3, v31, v3
	v_add_f32_e32 v31, v37, v36
	v_add_f32_e32 v31, v31, v3
	s_nop 0
	ds_read_b128 v[36:39], v2 offset:7888
	ds_read_b128 v[46:49], v2 offset:7904
	ds_read_b128 v[50:53], v2 offset:7920
	ds_read_b128 v[60:63], v2 offset:7936
	ds_read_b128 v[72:75], v2 offset:7952
	ds_read_b128 v[76:79], v2 offset:7968
	ds_read_b128 v[144:147], v2 offset:7984
	ds_read_b128 v[152:155], v2 offset:8000
	s_waitcnt lgkmcnt(14)
	v_fma_f32 v3, -v195, v32, v223
	v_fma_f32 v32, -v17, v33, 0
	v_fma_f32 v33, -v15, v34, 0
	v_fma_f32 v34, -v13, v35, 0
	s_waitcnt lgkmcnt(13)
	v_fma_f32 v3, -v11, v42, v3
	v_fma_f32 v32, -v9, v43, v32
	v_fma_f32 v33, -v7, v44, v33
	v_fma_f32 v34, -v4, v45, v34
	s_waitcnt lgkmcnt(12)
	v_fma_f32 v3, -v5, v56, v3
	v_fma_f32 v32, -v6, v57, v32
	v_fma_f32 v33, -v8, v58, v33
	v_fma_f32 v34, -v10, v59, v34
	s_waitcnt lgkmcnt(11)
	v_fma_f32 v3, -v12, v64, v3
	v_fma_f32 v32, -v14, v65, v32
	v_fma_f32 v33, -v16, v66, v33
	v_fma_f32 v34, -v18, v67, v34
	s_waitcnt lgkmcnt(10)
	v_fma_f32 v3, -v19, v68, v3
	v_fma_f32 v32, -v20, v69, v32
	v_fma_f32 v33, -v21, v70, v33
	v_fma_f32 v34, -v22, v71, v34
	s_waitcnt lgkmcnt(9)
	v_fma_f32 v3, -v23, v140, v3
	v_fma_f32 v32, -v24, v141, v32
	v_fma_f32 v33, -v25, v142, v33
	v_fma_f32 v34, -v27, v143, v34
	s_waitcnt lgkmcnt(8)
	v_fma_f32 v3, -v28, v148, v3
	v_fma_f32 v32, -v29, v149, v32
	v_fma_f32 v33, -v30, v150, v33
	v_fma_f32 v34, -v151, v31, v34
	v_add_f32_e32 v3, v32, v3
	v_add_f32_e32 v32, v34, v33
	v_add_f32_e32 v32, v32, v3
	s_waitcnt lgkmcnt(7)
	v_fma_f32 v33, -v17, v37, 0
	ds_read_b128 v[40:43], v2 offset:8160
	ds_read_b128 v[54:57], v2 offset:8176
	ds_read_b128 v[64:67], v2 offset:8192
	ds_read_b128 v[68:71], v2 offset:8208
	ds_read_b128 v[140:143], v2 offset:8224
	ds_read_b128 v[148:151], v2 offset:8240
	s_waitcnt lgkmcnt(6)
	ds_read_b128 v[154:157], v2 offset:8256
	ds_read_b128 v[158:161], v2 offset:8272
	v_fma_f32 v3, -v195, v36, v224
	v_fma_f32 v34, -v15, v38, 0
	v_fma_f32 v35, -v13, v39, 0
	v_fma_f32 v3, -v11, v46, v3
	v_fma_f32 v33, -v9, v47, v33
	v_fma_f32 v34, -v7, v48, v34
	v_fma_f32 v35, -v4, v49, v35
	v_fma_f32 v3, -v5, v50, v3
	v_fma_f32 v33, -v6, v51, v33
	v_fma_f32 v34, -v8, v52, v34
	v_fma_f32 v35, -v10, v53, v35
	v_fma_f32 v3, -v12, v60, v3
	v_fma_f32 v33, -v14, v61, v33
	v_fma_f32 v34, -v16, v62, v34
	v_fma_f32 v35, -v18, v63, v35
	v_fma_f32 v3, -v19, v72, v3
	v_fma_f32 v33, -v20, v73, v33
	v_fma_f32 v34, -v21, v74, v34
	v_fma_f32 v35, -v22, v75, v35
	v_fma_f32 v3, -v23, v76, v3
	v_fma_f32 v33, -v24, v77, v33
	v_fma_f32 v34, -v25, v78, v34
	v_fma_f32 v35, -v27, v79, v35
	v_fma_f32 v3, -v28, v144, v3
	v_fma_f32 v33, -v29, v145, v33
	v_fma_f32 v34, -v30, v146, v34
	v_fma_f32 v35, -v31, v147, v35
	v_fma_f32 v3, -v152, v32, v3
	v_add_f32_e32 v3, v33, v3
	v_add_f32_e32 v33, v35, v34
	v_add_f32_e32 v33, v33, v3
	s_waitcnt lgkmcnt(7)
	v_fma_f32 v34, -v17, v41, 0
	ds_read_b128 v[36:39], v2 offset:8432
	ds_read_b128 v[44:47], v2 offset:8448
	ds_read_b128 v[48:51], v2 offset:8464
	ds_read_b128 v[58:61], v2 offset:8480
	ds_read_b128 v[72:75], v2 offset:8496
	ds_read_b128 v[76:79], v2 offset:8512
	ds_read_b128 v[144:147], v2 offset:8528
	s_waitcnt lgkmcnt(7)
	ds_read_b128 v[160:163], v2 offset:8544
	v_fma_f32 v3, -v195, v40, v225
	v_fma_f32 v35, -v15, v42, 0
	v_fma_f32 v40, -v13, v43, 0
	v_fma_f32 v3, -v11, v54, v3
	v_fma_f32 v34, -v9, v55, v34
	v_fma_f32 v35, -v7, v56, v35
	v_fma_f32 v40, -v4, v57, v40
	v_fma_f32 v3, -v5, v64, v3
	v_fma_f32 v34, -v6, v65, v34
	v_fma_f32 v35, -v8, v66, v35
	v_fma_f32 v40, -v10, v67, v40
	v_fma_f32 v3, -v12, v68, v3
	v_fma_f32 v34, -v14, v69, v34
	v_fma_f32 v35, -v16, v70, v35
	v_fma_f32 v40, -v18, v71, v40
	v_fma_f32 v3, -v19, v140, v3
	v_fma_f32 v34, -v20, v141, v34
	v_fma_f32 v35, -v21, v142, v35
	v_fma_f32 v40, -v22, v143, v40
	v_fma_f32 v3, -v23, v148, v3
	v_fma_f32 v34, -v24, v149, v34
	v_fma_f32 v35, -v25, v150, v35
	v_fma_f32 v40, -v27, v151, v40
	v_fma_f32 v3, -v28, v154, v3
	v_fma_f32 v34, -v29, v155, v34
	v_fma_f32 v35, -v30, v156, v35
	v_fma_f32 v40, -v31, v157, v40
	v_fma_f32 v3, -v32, v158, v3
	v_fma_f32 v34, -v159, v33, v34
	v_add_f32_e32 v3, v34, v3
	v_add_f32_e32 v34, v40, v35
	v_add_f32_e32 v34, v34, v3
	s_waitcnt lgkmcnt(7)
	v_fma_f32 v3, -v17, v37, 0
	v_fma_f32 v2, -v195, v36, v226
	v_fma_f32 v35, -v15, v38, 0
	v_fma_f32 v36, -v13, v39, 0
	s_waitcnt lgkmcnt(6)
	v_fma_f32 v2, -v11, v44, v2
	v_fma_f32 v3, -v9, v45, v3
	v_fma_f32 v35, -v7, v46, v35
	v_fma_f32 v36, -v4, v47, v36
	s_waitcnt lgkmcnt(5)
	v_fma_f32 v2, -v5, v48, v2
	v_fma_f32 v3, -v6, v49, v3
	v_fma_f32 v35, -v8, v50, v35
	v_fma_f32 v36, -v10, v51, v36
	s_waitcnt lgkmcnt(4)
	v_fma_f32 v2, -v12, v58, v2
	v_fma_f32 v3, -v14, v59, v3
	v_fma_f32 v35, -v16, v60, v35
	v_fma_f32 v36, -v18, v61, v36
	s_waitcnt lgkmcnt(3)
	v_fma_f32 v2, -v19, v72, v2
	v_fma_f32 v3, -v20, v73, v3
	v_fma_f32 v35, -v21, v74, v35
	v_fma_f32 v36, -v22, v75, v36
	s_waitcnt lgkmcnt(2)
	v_fma_f32 v2, -v23, v76, v2
	v_fma_f32 v3, -v24, v77, v3
	v_fma_f32 v35, -v25, v78, v35
	v_fma_f32 v36, -v27, v79, v36
	s_waitcnt lgkmcnt(1)
	v_fma_f32 v2, -v28, v144, v2
	v_fma_f32 v3, -v29, v145, v3
	v_fma_f32 v35, -v30, v146, v35
	v_fma_f32 v36, -v31, v147, v36
	s_waitcnt lgkmcnt(0)
	v_fma_f32 v2, -v32, v160, v2
	v_fma_f32 v3, -v33, v161, v3
	v_fma_f32 v35, -v162, v34, v35
	v_add_f32_e32 v2, v3, v2
	v_add_f32_e32 v3, v36, v35
	v_add_f32_e32 v35, v3, v2
	ds_read2st64_b32 v[2:3], v186 offset1:2
	s_waitcnt lgkmcnt(0)
	v_mul_f32_e32 v36, v2, v3
	v_mul_f32_e32 v3, v195, v2
	v_cvt_pk_bf16_f32 v3, v3, v3
	ds_write_b16 v190, v3
	v_mul_f32_e32 v3, v195, v36
	v_cvt_pk_bf16_f32 v3, v3, v3
	ds_write_b16 v190, v3 offset:64
	v_add_u32_e32 v3, v171, v189
	s_and_saveexec_b64 s[18:19], s[8:9]
	ds_write_b16 v3, v227 offset:128
	s_or_b64 exec, exec, s[18:19]
	v_mul_f32_e32 v37, v17, v2
	v_cvt_pk_bf16_f32 v37, v37, v37
	ds_write_b16 v190, v37 offset:272
	v_mul_f32_e32 v37, v17, v36
	v_cvt_pk_bf16_f32 v37, v37, v37
	ds_write_b16 v190, v37 offset:336
	s_and_saveexec_b64 s[18:19], s[8:9]
	v_cvt_pk_bf16_f32 v17, -v17, -v17
	ds_write_b16 v3, v17 offset:400
	s_or_b64 exec, exec, s[18:19]
	v_mul_f32_e32 v17, v15, v2
	v_cvt_pk_bf16_f32 v17, v17, v17
	ds_write_b16 v190, v17 offset:544
	v_mul_f32_e32 v17, v15, v36
	v_cvt_pk_bf16_f32 v17, v17, v17
	ds_write_b16 v190, v17 offset:608
	s_and_saveexec_b64 s[18:19], s[8:9]
	v_cvt_pk_bf16_f32 v15, -v15, -v15
	ds_write_b16 v3, v15 offset:672
	s_or_b64 exec, exec, s[18:19]
	v_mul_f32_e32 v15, v13, v2
	v_cvt_pk_bf16_f32 v15, v15, v15
	ds_write_b16 v190, v15 offset:816
	v_mul_f32_e32 v15, v13, v36
	v_cvt_pk_bf16_f32 v15, v15, v15
	ds_write_b16 v190, v15 offset:880
	s_and_saveexec_b64 s[18:19], s[8:9]
	v_cvt_pk_bf16_f32 v13, -v13, -v13
	ds_write_b16 v3, v13 offset:944
	s_or_b64 exec, exec, s[18:19]
	v_mul_f32_e32 v13, v11, v2
	v_cvt_pk_bf16_f32 v13, v13, v13
	ds_write_b16 v190, v13 offset:1088
	v_mul_f32_e32 v13, v11, v36
	v_cvt_pk_bf16_f32 v13, v13, v13
	ds_write_b16 v190, v13 offset:1152
	s_and_saveexec_b64 s[18:19], s[8:9]
	v_cvt_pk_bf16_f32 v11, -v11, -v11
	ds_write_b16 v3, v11 offset:1216
	s_or_b64 exec, exec, s[18:19]
	v_mul_f32_e32 v11, v9, v2
	v_cvt_pk_bf16_f32 v11, v11, v11
	ds_write_b16 v190, v11 offset:1360
	v_mul_f32_e32 v11, v9, v36
	v_cvt_pk_bf16_f32 v11, v11, v11
	ds_write_b16 v190, v11 offset:1424
	s_and_saveexec_b64 s[18:19], s[8:9]
	v_cvt_pk_bf16_f32 v9, -v9, -v9
	ds_write_b16 v3, v9 offset:1488
	s_or_b64 exec, exec, s[18:19]
	v_mul_f32_e32 v9, v7, v2
	v_cvt_pk_bf16_f32 v9, v9, v9
	ds_write_b16 v190, v9 offset:1632
	v_mul_f32_e32 v9, v7, v36
	v_cvt_pk_bf16_f32 v9, v9, v9
	ds_write_b16 v190, v9 offset:1696
	s_and_saveexec_b64 s[18:19], s[8:9]
	v_cvt_pk_bf16_f32 v7, -v7, -v7
	ds_write_b16 v3, v7 offset:1760
	s_or_b64 exec, exec, s[18:19]
	v_mul_f32_e32 v7, v4, v2
	v_cvt_pk_bf16_f32 v7, v7, v7
	ds_write_b16 v190, v7 offset:1904
	v_mul_f32_e32 v7, v4, v36
	v_cvt_pk_bf16_f32 v7, v7, v7
	ds_write_b16 v190, v7 offset:1968
	s_and_saveexec_b64 s[18:19], s[8:9]
	v_cvt_pk_bf16_f32 v4, -v4, -v4
	ds_write_b16 v3, v4 offset:2032
	s_or_b64 exec, exec, s[18:19]
	v_mul_f32_e32 v4, v5, v2
	v_cvt_pk_bf16_f32 v4, v4, v4
	ds_write_b16 v190, v4 offset:2176
	v_mul_f32_e32 v4, v5, v36
	v_cvt_pk_bf16_f32 v4, v4, v4
	ds_write_b16 v190, v4 offset:2240
	s_and_saveexec_b64 s[18:19], s[8:9]
	v_cvt_pk_bf16_f32 v4, -v5, -v5
	ds_write_b16 v3, v4 offset:2304
	s_or_b64 exec, exec, s[18:19]
	v_mul_f32_e32 v4, v6, v2
	v_cvt_pk_bf16_f32 v4, v4, v4
	ds_write_b16 v190, v4 offset:2448
	v_mul_f32_e32 v4, v6, v36
	v_cvt_pk_bf16_f32 v4, v4, v4
	ds_write_b16 v190, v4 offset:2512
	s_and_saveexec_b64 s[18:19], s[8:9]
	v_cvt_pk_bf16_f32 v4, -v6, -v6
	ds_write_b16 v3, v4 offset:2576
	s_or_b64 exec, exec, s[18:19]
	v_mul_f32_e32 v4, v8, v2
	v_cvt_pk_bf16_f32 v4, v4, v4
	ds_write_b16 v190, v4 offset:2720
	v_mul_f32_e32 v4, v8, v36
	v_cvt_pk_bf16_f32 v4, v4, v4
	ds_write_b16 v190, v4 offset:2784
	s_and_saveexec_b64 s[18:19], s[8:9]
	v_cvt_pk_bf16_f32 v4, -v8, -v8
	ds_write_b16 v3, v4 offset:2848
	s_or_b64 exec, exec, s[18:19]
	v_mul_f32_e32 v4, v10, v2
	v_cvt_pk_bf16_f32 v4, v4, v4
	ds_write_b16 v190, v4 offset:2992
	v_mul_f32_e32 v4, v10, v36
	v_cvt_pk_bf16_f32 v4, v4, v4
	ds_write_b16 v190, v4 offset:3056
	s_and_saveexec_b64 s[18:19], s[8:9]
	v_cvt_pk_bf16_f32 v4, -v10, -v10
	ds_write_b16 v3, v4 offset:3120
	s_or_b64 exec, exec, s[18:19]
	v_mul_f32_e32 v4, v12, v2
	v_cvt_pk_bf16_f32 v4, v4, v4
	ds_write_b16 v190, v4 offset:3264
	v_mul_f32_e32 v4, v12, v36
	v_cvt_pk_bf16_f32 v4, v4, v4
	ds_write_b16 v190, v4 offset:3328
	s_and_saveexec_b64 s[18:19], s[8:9]
	v_cvt_pk_bf16_f32 v4, -v12, -v12
	ds_write_b16 v3, v4 offset:3392
	s_or_b64 exec, exec, s[18:19]
	v_mul_f32_e32 v4, v14, v2
	v_cvt_pk_bf16_f32 v4, v4, v4
	ds_write_b16 v190, v4 offset:3536
	v_mul_f32_e32 v4, v14, v36
	v_cvt_pk_bf16_f32 v4, v4, v4
	ds_write_b16 v190, v4 offset:3600
	s_and_saveexec_b64 s[18:19], s[8:9]
	v_cvt_pk_bf16_f32 v4, -v14, -v14
	ds_write_b16 v3, v4 offset:3664
	s_or_b64 exec, exec, s[18:19]
	v_mul_f32_e32 v4, v16, v2
	v_cvt_pk_bf16_f32 v4, v4, v4
	ds_write_b16 v190, v4 offset:3808
	v_mul_f32_e32 v4, v16, v36
	v_cvt_pk_bf16_f32 v4, v4, v4
	ds_write_b16 v190, v4 offset:3872
	s_and_saveexec_b64 s[18:19], s[8:9]
	v_cvt_pk_bf16_f32 v4, -v16, -v16
	ds_write_b16 v3, v4 offset:3936
	s_or_b64 exec, exec, s[18:19]
	v_mul_f32_e32 v4, v18, v2
	v_cvt_pk_bf16_f32 v4, v4, v4
	ds_write_b16 v190, v4 offset:4080
	v_mul_f32_e32 v4, v18, v36
	v_cvt_pk_bf16_f32 v4, v4, v4
	ds_write_b16 v190, v4 offset:4144
	s_and_saveexec_b64 s[18:19], s[8:9]
	v_cvt_pk_bf16_f32 v4, -v18, -v18
	ds_write_b16 v3, v4 offset:4208
	s_or_b64 exec, exec, s[18:19]
	v_mul_f32_e32 v4, v19, v2
	v_cvt_pk_bf16_f32 v4, v4, v4
	ds_write_b16 v190, v4 offset:4352
	v_mul_f32_e32 v4, v19, v36
	v_cvt_pk_bf16_f32 v4, v4, v4
	ds_write_b16 v190, v4 offset:4416
	s_and_saveexec_b64 s[18:19], s[8:9]
	v_cvt_pk_bf16_f32 v4, -v19, -v19
	ds_write_b16 v3, v4 offset:4480
	s_or_b64 exec, exec, s[18:19]
	v_mul_f32_e32 v4, v20, v2
	v_cvt_pk_bf16_f32 v4, v4, v4
	ds_write_b16 v190, v4 offset:4624
	v_mul_f32_e32 v4, v20, v36
	v_cvt_pk_bf16_f32 v4, v4, v4
	ds_write_b16 v190, v4 offset:4688
	s_and_saveexec_b64 s[18:19], s[8:9]
	v_cvt_pk_bf16_f32 v4, -v20, -v20
	ds_write_b16 v3, v4 offset:4752
	s_or_b64 exec, exec, s[18:19]
	v_mul_f32_e32 v4, v21, v2
	v_cvt_pk_bf16_f32 v4, v4, v4
	ds_write_b16 v190, v4 offset:4896
	v_mul_f32_e32 v4, v21, v36
	v_cvt_pk_bf16_f32 v4, v4, v4
	ds_write_b16 v190, v4 offset:4960
	s_and_saveexec_b64 s[18:19], s[8:9]
	v_cvt_pk_bf16_f32 v4, -v21, -v21
	ds_write_b16 v3, v4 offset:5024
	s_or_b64 exec, exec, s[18:19]
	v_mul_f32_e32 v4, v22, v2
	v_cvt_pk_bf16_f32 v4, v4, v4
	ds_write_b16 v190, v4 offset:5168
	v_mul_f32_e32 v4, v22, v36
	v_cvt_pk_bf16_f32 v4, v4, v4
	ds_write_b16 v190, v4 offset:5232
	s_and_saveexec_b64 s[18:19], s[8:9]
	v_cvt_pk_bf16_f32 v4, -v22, -v22
	ds_write_b16 v3, v4 offset:5296
	s_or_b64 exec, exec, s[18:19]
	v_mul_f32_e32 v4, v23, v2
	v_cvt_pk_bf16_f32 v4, v4, v4
	ds_write_b16 v190, v4 offset:5440
	v_mul_f32_e32 v4, v23, v36
	v_cvt_pk_bf16_f32 v4, v4, v4
	ds_write_b16 v190, v4 offset:5504
	s_and_saveexec_b64 s[18:19], s[8:9]
	v_cvt_pk_bf16_f32 v4, -v23, -v23
	ds_write_b16 v3, v4 offset:5568
	s_or_b64 exec, exec, s[18:19]
	v_mul_f32_e32 v4, v24, v2
	v_cvt_pk_bf16_f32 v4, v4, v4
	ds_write_b16 v190, v4 offset:5712
	v_mul_f32_e32 v4, v24, v36
	v_cvt_pk_bf16_f32 v4, v4, v4
	ds_write_b16 v190, v4 offset:5776
	s_and_saveexec_b64 s[18:19], s[8:9]
	v_cvt_pk_bf16_f32 v4, -v24, -v24
	ds_write_b16 v3, v4 offset:5840
	s_or_b64 exec, exec, s[18:19]
	v_mul_f32_e32 v4, v25, v2
	v_cvt_pk_bf16_f32 v4, v4, v4
	ds_write_b16 v190, v4 offset:5984
	v_mul_f32_e32 v4, v25, v36
	v_cvt_pk_bf16_f32 v4, v4, v4
	ds_write_b16 v190, v4 offset:6048
	s_and_saveexec_b64 s[18:19], s[8:9]
	v_cvt_pk_bf16_f32 v4, -v25, -v25
	ds_write_b16 v3, v4 offset:6112
	s_or_b64 exec, exec, s[18:19]
	v_mul_f32_e32 v4, v27, v2
	v_cvt_pk_bf16_f32 v4, v4, v4
	ds_write_b16 v190, v4 offset:6256
	v_mul_f32_e32 v4, v27, v36
	v_cvt_pk_bf16_f32 v4, v4, v4
	ds_write_b16 v190, v4 offset:6320
	s_and_saveexec_b64 s[18:19], s[8:9]
	v_cvt_pk_bf16_f32 v4, -v27, -v27
	ds_write_b16 v3, v4 offset:6384
	s_or_b64 exec, exec, s[18:19]
	v_mul_f32_e32 v4, v28, v2
	v_cvt_pk_bf16_f32 v4, v4, v4
	ds_write_b16 v190, v4 offset:6528
	v_mul_f32_e32 v4, v28, v36
	v_cvt_pk_bf16_f32 v4, v4, v4
	ds_write_b16 v190, v4 offset:6592
	s_and_saveexec_b64 s[18:19], s[8:9]
	v_cvt_pk_bf16_f32 v4, -v28, -v28
	ds_write_b16 v3, v4 offset:6656
	s_or_b64 exec, exec, s[18:19]
	v_mul_f32_e32 v4, v29, v2
	v_cvt_pk_bf16_f32 v4, v4, v4
	ds_write_b16 v190, v4 offset:6800
	v_mul_f32_e32 v4, v29, v36
	v_cvt_pk_bf16_f32 v4, v4, v4
	ds_write_b16 v190, v4 offset:6864
	s_and_saveexec_b64 s[18:19], s[8:9]
	v_cvt_pk_bf16_f32 v4, -v29, -v29
	ds_write_b16 v3, v4 offset:6928
	s_or_b64 exec, exec, s[18:19]
	v_mul_f32_e32 v4, v30, v2
	v_cvt_pk_bf16_f32 v4, v4, v4
	ds_write_b16 v190, v4 offset:7072
	v_mul_f32_e32 v4, v30, v36
	v_cvt_pk_bf16_f32 v4, v4, v4
	ds_write_b16 v190, v4 offset:7136
	s_and_saveexec_b64 s[18:19], s[8:9]
	v_cvt_pk_bf16_f32 v4, -v30, -v30
	ds_write_b16 v3, v4 offset:7200
	s_or_b64 exec, exec, s[18:19]
	v_mul_f32_e32 v4, v31, v2
	v_cvt_pk_bf16_f32 v4, v4, v4
	ds_write_b16 v190, v4 offset:7344
	v_mul_f32_e32 v4, v31, v36
	v_cvt_pk_bf16_f32 v4, v4, v4
	ds_write_b16 v190, v4 offset:7408
	s_and_saveexec_b64 s[18:19], s[8:9]
	v_cvt_pk_bf16_f32 v4, -v31, -v31
	ds_write_b16 v3, v4 offset:7472
	s_or_b64 exec, exec, s[18:19]
	v_mul_f32_e32 v4, v32, v2
	v_cvt_pk_bf16_f32 v4, v4, v4
	ds_write_b16 v190, v4 offset:7616
	v_mul_f32_e32 v4, v32, v36
	v_cvt_pk_bf16_f32 v4, v4, v4
	ds_write_b16 v190, v4 offset:7680
	s_and_saveexec_b64 s[18:19], s[8:9]
	v_cvt_pk_bf16_f32 v4, -v32, -v32
	ds_write_b16 v3, v4 offset:7744
	s_or_b64 exec, exec, s[18:19]
	v_mul_f32_e32 v4, v33, v2
	v_cvt_pk_bf16_f32 v4, v4, v4
	ds_write_b16 v190, v4 offset:7888
	v_mul_f32_e32 v4, v33, v36
	v_cvt_pk_bf16_f32 v4, v4, v4
	ds_write_b16 v190, v4 offset:7952
	s_and_saveexec_b64 s[18:19], s[8:9]
	v_cvt_pk_bf16_f32 v4, -v33, -v33
	ds_write_b16 v3, v4 offset:8016
	s_or_b64 exec, exec, s[18:19]
	v_mul_f32_e32 v4, v34, v2
	v_cvt_pk_bf16_f32 v4, v4, v4
	ds_write_b16 v190, v4 offset:8160
	v_mul_f32_e32 v4, v34, v36
	v_cvt_pk_bf16_f32 v4, v4, v4
	ds_write_b16 v190, v4 offset:8224
	s_and_saveexec_b64 s[18:19], s[8:9]
	v_cvt_pk_bf16_f32 v4, -v34, -v34
	ds_write_b16 v3, v4 offset:8288
	s_or_b64 exec, exec, s[18:19]
	v_mul_f32_e32 v2, v35, v2
	v_cvt_pk_bf16_f32 v2, v2, v2
	ds_write_b16 v190, v2 offset:8432
	v_mul_f32_e32 v2, v35, v36
	v_cvt_pk_bf16_f32 v2, v2, v2
	ds_write_b16 v190, v2 offset:8496
	s_and_saveexec_b64 s[18:19], s[8:9]
	v_cvt_pk_bf16_f32 v2, -v35, -v35
	ds_write_b16 v3, v2 offset:8560
	s_or_b64 exec, exec, s[18:19]
